# v20 + mixer-B row steps skipped by waves whose 32 queries are all row-masked for that key row
# speedup vs baseline: 1.0047x; 1.0033x over previous
; #define LAS __attribute__((address_space(3)))
; template <int MASK, bool FIX> ...
;     const LAS unsigned char* kp = buf + (kvoff + r32) * KSTR + hi * 16;
;     f32x16 s = cinit;
; #pragma unroll
;     for (int d0 = 0; d0 < 4; ++d0) { const bf16x8 kf = *(const LAS bf16x8*)(kp + d0 * 32); s = __builtin_amdgcn_mfma_f32_32x32x16_bf16(kf, qf[d0], s, 0, 0, 0); }
;     const float NEG = -INFINITY;
;     if (MASK == 3) {
;         float bv[16];
; #pragma unroll
;         for (int r = 0; r < 16; ++r) bv[r] = rpbl[bidx0 + (r & 3) + 8 * (r >> 2)];
; #pragma unroll
;         for (int r = 0; r < 16; ++r) asm volatile("" : "+v"(bv[r]));
; #pragma unroll
;         for (int r = 0; r < 16; ++r) s[r] = ((vmask >> r) & 1u) ? (s[r] + bv[r]) : NEG;
;     }
; #pragma unroll
;     for (int r = 0; r < 16; ++r) {
;         const int kl0 = (r & 3) + 8 * (r >> 2);
;         if (MASK == 1) { if (kl0 + 4 * hi < r32) s[r] = NEG; }
;         if (MASK == 2) { if (kl0 + 4 * hi > r32) s[r] = NEG; }
;     }
;     if (!FIX) {
;         float mx = fmaxf(fmaxf(s[0], s[1]), fmaxf(s[2], s[3]));
; #pragma unroll
;         for (int r = 4; r < 16; r += 4) mx = fmaxf(mx, fmaxf(fmaxf(s[r], s[r + 1]), fmaxf(s[r + 2], s[r + 3])));
;         mx = swap_max(mx);
;         const float mnew = fmaxf(m, mx);
;         const float msafe = (mnew == NEG) ? 0.f : mnew;
;         if (__any(mnew > m)) {
;             const float alpha = __builtin_amdgcn_exp2f(m - msafe);
;             l *= alpha;
; #pragma unroll
;             for (int r = 0; r < 16; ++r) { o0[r] *= alpha; o1[r] *= alpha; }
;         }
;         m = mnew;
;         float ls = 0.f;
; #pragma unroll
;         for (int r = 0; r < 16; ++r) { s[r] = __builtin_amdgcn_exp2f(s[r] - msafe); ls += s[r]; }
;         l += ls;
;     } else {
; #pragma unroll
;         for (int r = 0; r < 16; ++r) s[r] = __builtin_amdgcn_exp2f(s[r]);
;         l += (((s[0] + s[1]) + (s[2] + s[3])) + ((s[4] + s[5]) + (s[6] + s[7]))) + (((s[8] + s[9]) + (s[10] + s[11])) + ((s[12] + s[13]) + (s[14] + s[15])));
;     }
;     u32x4 pw0, pw1;
;     pw0.x = cvtpk(s[0], s[1]); pw0.y = cvtpk(s[2], s[3]); pw0.z = cvtpk(s[4], s[5]); pw0.w = cvtpk(s[6], s[7]);
;     pw1.x = cvtpk(s[8], s[9]); pw1.y = cvtpk(s[10], s[11]); pw1.z = cvtpk(s[12], s[13]); pw1.w = cvtpk(s[14], s[15]);
;     const bf16x8 p0 = __builtin_bit_cast(bf16x8, pw0), p1 = __builtin_bit_cast(bf16x8, pw1);
.LBB0_727:
	s_bitcmp1_b32 s10, 0
	s_cselect_b32 s8, 0x4480, 0
	s_add_i32 s13, s48, s10
	v_add_u32_e32 v64, s10, v81
	s_add_i32 s55, s10, 1
	s_add_i32 s11, s54, s10
	s_add_i32 s14, s8, 0
	s_add_i32 s12, s13, 1
	v_cmp_gt_u32_e32 vcc, 8, v64
	v_cmp_lt_u32_e64 s[8:9], s13, v15
	s_cmp_lt_i32 s10, s49
	v_cndmask_b32_e32 v212, v230, v82, vcc
	v_cmp_gt_u32_e32 vcc, s13, v80
	s_cselect_b32 s10, s12, s11
	s_cselect_b32 s11, s51, s52
	s_and_b64 s[8:9], s[44:45], s[8:9]
	v_add_u32_e32 v65, s14, v178
	s_lshl_b32 s10, s10, 6
	s_or_b64 s[8:9], s[8:9], vcc
	v_add_u32_e32 v66, s14, v194
	s_waitcnt vmcnt(1)
	ds_write_b128 v65, v[96:99]
	s_waitcnt vmcnt(0)
	ds_write_b128 v66, v[100:103] offset:9216
	v_cndmask_b32_e64 v212, v212, v230, s[8:9]
	s_add_i32 s10, s10, s11
	v_add3_u32 v67, s14, v152, v189
	v_mad_i64_i32 v[240:241], s[8:9], s10, v156, v[104:105]
	s_nop 1
	global_load_dwordx4 v[96:99], v[240:241], off offset:2560
	global_load_dwordx4 v[100:103], v[240:241], off offset:3584
	s_waitcnt lgkmcnt(0)
	s_barrier
	v_cmp_eq_u32_e64 s[8:9], v212, v230
	s_nop 1
	s_cmp_eq_u64 s[8:9], exec
	s_cbranch_scc1 .Lmb_skip
	ds_read_b128 v[84:87], v67
	ds_read_b128 v[88:91], v67 offset:32
	ds_read_b128 v[106:109], v67 offset:64
	ds_read_b128 v[110:113], v67 offset:96
	ds_read2_b32 v[118:119], v212 offset1:1
	ds_read2_b32 v[120:121], v212 offset0:2 offset1:3
	ds_read2_b32 v[122:123], v212 offset0:8 offset1:9
	ds_read2_b32 v[124:125], v212 offset0:10 offset1:11
	ds_read2_b32 v[126:127], v212 offset0:16 offset1:17
	ds_read2_b32 v[128:129], v212 offset0:18 offset1:19
	ds_read2_b32 v[130:131], v212 offset0:24 offset1:25
	s_waitcnt lgkmcnt(13)
	ds_read2_b32 v[132:133], v212 offset0:26 offset1:27
	v_add3_u32 v68, s14, v190, v153
	v_add3_u32 v83, v68, v191, v192
	s_waitcnt lgkmcnt(11)
	v_mfma_f32_32x32x16_bf16 v[64:79], v[84:87], v[2:5], v[196:211]
	s_waitcnt lgkmcnt(7)
	s_waitcnt lgkmcnt(6)
	s_waitcnt lgkmcnt(5)
	s_waitcnt lgkmcnt(4)
	v_mfma_f32_32x32x16_bf16 v[64:79], v[88:91], v[6:9], v[64:79]
	s_waitcnt lgkmcnt(3)
	s_waitcnt lgkmcnt(2)
	s_waitcnt lgkmcnt(1)
	v_mfma_f32_32x32x16_bf16 v[64:79], v[106:109], v[10:13], v[64:79]
	s_waitcnt lgkmcnt(0)
	ds_read_b64_tr_b16 v[84:85], v83 offset:9216
	v_mfma_f32_32x32x16_bf16 v[64:79], v[110:113], v[92:95], v[64:79]
	ds_read_b64_tr_b16 v[86:87], v83 offset:9728
	ds_read_b64_tr_b16 v[88:89], v83 offset:10240
	ds_read_b64_tr_b16 v[90:91], v83 offset:10752
	ds_read_b64_tr_b16 v[106:107], v83 offset:13376
	ds_read_b64_tr_b16 v[108:109], v83 offset:13888
	ds_read_b64_tr_b16 v[114:115], v83 offset:14400
	ds_read_b64_tr_b16 v[116:117], v83 offset:14912
	s_nop 5
	v_pk_add_f32 v[214:215], v[118:119], v[64:65]
	v_pk_add_f32 v[216:217], v[120:121], v[66:67]
	v_pk_add_f32 v[218:219], v[122:123], v[68:69]
	v_pk_add_f32 v[220:221], v[124:125], v[70:71]
	v_pk_add_f32 v[222:223], v[126:127], v[72:73]
	v_pk_add_f32 v[224:225], v[128:129], v[74:75]
	v_pk_add_f32 v[226:227], v[130:131], v[76:77]
	v_pk_add_f32 v[228:229], v[132:133], v[78:79]
	v_exp_f32_e32 v68, v214
	v_exp_f32_e32 v70, v215
	v_exp_f32_e32 v72, v216
	v_exp_f32_e32 v74, v217
	v_exp_f32_e32 v76, v218
	v_exp_f32_e32 v78, v219
	v_exp_f32_e32 v110, v220
	v_exp_f32_e32 v112, v221
	v_cvt_pk_bf16_f32 v64, v68, v70
	v_cvt_pk_bf16_f32 v65, v72, v74
	v_cvt_pk_bf16_f32 v66, v76, v78
	v_cvt_pk_bf16_f32 v67, v110, v112
	s_nop 0
	s_waitcnt lgkmcnt(6)
	v_mfma_f32_32x32x16_bf16 v[32:47], v[84:87], v[64:67], v[32:47]
	s_waitcnt lgkmcnt(2)
	v_mfma_f32_32x32x16_bf16 v[48:63], v[106:109], v[64:67], v[48:63]
	v_exp_f32_e32 v69, v222
	v_exp_f32_e32 v71, v223
	v_exp_f32_e32 v73, v224
	v_exp_f32_e32 v75, v225
	v_exp_f32_e32 v77, v226
	v_exp_f32_e32 v79, v227
	v_exp_f32_e32 v111, v228
	v_exp_f32_e32 v113, v229
	v_cvt_pk_bf16_f32 v64, v69, v71
	v_cvt_pk_bf16_f32 v65, v73, v75
	v_cvt_pk_bf16_f32 v66, v77, v79
	v_cvt_pk_bf16_f32 v67, v111, v113
	v_pk_add_f32 v[68:69], v[68:69], v[70:71]
	v_pk_add_f32 v[72:73], v[72:73], v[74:75]
	v_mfma_f32_32x32x16_bf16 v[32:47], v[88:91], v[64:67], v[32:47]
	v_pk_add_f32 v[76:77], v[76:77], v[78:79]
	v_pk_add_f32 v[110:111], v[110:111], v[112:113]
	s_mov_b32 s10, s55
	v_add_u32_e32 v82, 0x7c, v82
	s_cmp_eq_u32 s42, s55
	s_waitcnt lgkmcnt(0)
	v_mfma_f32_32x32x16_bf16 v[48:63], v[114:117], v[64:67], v[48:63]
	v_pk_add_f32 v[68:69], v[68:69], v[72:73]
	v_pk_add_f32 v[76:77], v[76:77], v[110:111]
	s_nop 0
	v_pk_add_f32 v[68:69], v[68:69], v[76:77]
	s_nop 0
	v_add_f32_e32 v64, v68, v69
	v_add_f32_e32 v0, v0, v64
	s_cbranch_scc0 .LBB0_727
	s_branch .Lmb_done
.Lmb_skip:
	s_mov_b32 s10, s55
	v_add_u32_e32 v82, 0x7c, v82
	s_cmp_eq_u32 s42, s55
	s_cbranch_scc0 .LBB0_727
.Lmb_done:
	s_add_i32 s11, s49, 1
	s_branch .LBB0_730
